# rw_phase PH12/PH16: next-row Y loads de-serialized, wait+unpack deferred to loop latch
# speedup vs baseline: 1.0053x; 1.0053x over previous
; DI void rw_phase(const RW& a, int NGW) {
;     ...
;         int rn = r + NGW;
;         if (a.skipctx) { while (rn < M && (rn % TP) >= TL) rn += NGW; }
;         if (rn < M) RW_LOAD(rn);
;         f32x4 gq[4], s1q[4], s2q[4];
;         if (a.Y) { const float* gt = a.modA + (size_t)mr * 6144 + a.gate_chunk * 1024;
; #pragma unroll
;             for (int j = 0; j < 4; ++j) gq[j] = *(const f32x4*)(gt + 4 * lane + 256 * j); }
;         if (a.H) { const float* sh = a.modB + (size_t)mr * 6144 + a.sh_chunk * 1024;
; #pragma unroll
;             for (int j = 0; j < 4; ++j) { s1q[j] = *(const f32x4*)(sh + 4 * lane + 256 * j); s2q[j] = *(const f32x4*)(sh + 1024 + 4 * lane + 256 * j); } }
;         if (a.Y) {
;             float ss = 0.f;
; #pragma unroll
;             for (int j = 0; j < 4; ++j) ss += (y[j][0] * y[j][0] + y[j][1] * y[j][1]) + (y[j][2] * y[j][2] + y[j][3] * y[j][3]);
;             const float rs = rsqrtf(wave_sum(ss) * (1.f / D) + EPS);
;             float* xo = (isctx ? a.xo_ctx : a.xo_lat) + xoff;
; #pragma unroll
;             for (int j = 0; j < 4; ++j) { x[j] = x[j] + gq[j] * (y[j] * rs * gpo[j]); *(f32x4*)(xo + 4 * lane + 256 * j) = x[j]; }
;         }
;         if (a.H) {
;             float ss = 0.f;
; #pragma unroll
;             for (int j = 0; j < 4; ++j) ss += (x[j][0] * x[j][0] + x[j][1] * x[j][1]) + (x[j][2] * x[j][2] + x[j][3] * x[j][3]);
;             const float rs = rsqrtf(wave_sum(ss) * (1.f / D) + EPS);
.LBB0_1015:
	s_ashr_i32 s65, s64, 31
	s_lshl_b64 s[64:65], s[64:65], 12
	s_add_u32 s64, s66, s64
	s_addc_u32 s65, s67, s65
	s_ashr_i32 s55, s54, 31
	v_lshl_add_u64 v[50:51], v[66:67], 2, s[64:65]
	s_lshl_b64 s[64:65], s[54:55], 11
	flat_load_dwordx4 v[62:65], v[50:51]
	flat_load_dwordx4 v[58:61], v[50:51] offset:1024
	flat_load_dwordx4 v[54:57], v[50:51] offset:2048
	s_nop 0
	flat_load_dwordx4 v[50:53], v[50:51] offset:3072
	v_lshl_add_u64 v[108:109], v[70:71], 0, s[64:65]
	flat_load_dwordx2 v[160:161], v[108:109]
	flat_load_dwordx2 v[162:163], v[108:109] offset:512
	flat_load_dwordx2 v[164:165], v[108:109] offset:1024
	flat_load_dwordx2 v[166:167], v[108:109] offset:1536
.LBB0_1016:
	s_ashr_i32 s61, s60, 31
	s_lshl_b64 s[62:63], s[62:63], 2
	s_add_u32 s64, s46, s62
	s_addc_u32 s65, s47, s63
	v_lshl_add_u64 v[112:113], s[64:65], 0, v[68:69]
	s_mov_b64 s[64:65], 0x2000
	v_add_co_u32_e32 v120, vcc, 0x2000, v112
	v_lshl_add_u64 v[124:125], v[112:113], 0, s[64:65]
	s_nop 0
	v_addc_co_u32_e32 v121, vcc, 0, v113, vcc
	flat_load_dwordx4 v[112:115], v[124:125] offset:1024
	flat_load_dwordx4 v[116:119], v[124:125] offset:2048
	s_nop 0
	flat_load_dwordx4 v[120:123], v[120:121]
	s_nop 0
	flat_load_dwordx4 v[124:127], v[124:125] offset:3072
	v_pk_mul_f32 v[128:129], v[86:87], v[86:87]
	v_pk_mul_f32 v[130:131], v[88:89], v[88:89]
	v_mov_b32_e32 v132, v128
	v_mov_b32_e32 v133, v131
	v_pk_mov_b32 v[128:129], v[128:129], v[130:131] op_sel:[1,0]
	v_pk_mul_f32 v[130:131], v[82:83], v[82:83]
	v_pk_add_f32 v[128:129], v[128:129], v[132:133]
	v_pk_mul_f32 v[132:133], v[84:85], v[84:85]
	v_mov_b32_e32 v134, v130
	v_mov_b32_e32 v135, v133
	v_pk_mov_b32 v[130:131], v[130:131], v[132:133] op_sel:[1,0]
	v_mul_f32_e32 v111, v74, v74
	v_pk_add_f32 v[130:131], v[130:131], v[134:135]
	v_mul_f32_e32 v132, v75, v75
	v_pk_add_f32 v[128:129], v[128:129], v[128:129] op_sel:[0,1] op_sel_hi:[1,0]
	v_pk_add_f32 v[130:131], v[130:131], v[130:131] op_sel:[0,1] op_sel_hi:[1,0]
	v_mov_b32_e32 v129, v111
	v_mov_b32_e32 v131, v132
	v_pk_add_f32 v[128:129], v[128:129], v[130:131]
	v_mul_f32_e32 v130, v79, v79
	v_mul_f32_e32 v133, v76, v76
	v_pk_fma_f32 v[130:131], v[78:79], v[78:79], v[130:131] op_sel_hi:[1,1,0]
	v_mul_f32_e32 v132, v81, v81
	v_mul_f32_e32 v134, v77, v77
	v_mov_b32_e32 v131, v133
	v_pk_fma_f32 v[132:133], v[80:81], v[80:81], v[132:133] op_sel_hi:[1,1,0]
	s_add_u32 s62, s70, s62
	v_mov_b32_e32 v133, v134
	v_pk_add_f32 v[130:131], v[130:131], v[132:133]
	s_addc_u32 s63, s71, s63
	v_pk_add_f32 v[128:129], v[128:129], v[130:131]
	s_movk_i32 s48, 0x3000
	v_add_f32_e32 v111, v128, v129
	ds_bpermute_b32 v128, v1, v111
	s_mov_b32 s53, 0x800000
	s_and_b64 s[58:59], s[58:59], exec
	s_cselect_b32 s49, s42, s50
	s_waitcnt lgkmcnt(0)
	v_add_f32_e32 v111, v111, v128
	ds_bpermute_b32 v128, v90, v111
	s_waitcnt lgkmcnt(0)
	v_add_f32_e32 v111, v111, v128
	ds_bpermute_b32 v128, v91, v111
	s_waitcnt lgkmcnt(0)
	v_add_f32_e32 v111, v111, v128
	ds_bpermute_b32 v130, v92, v111
	v_lshl_add_u64 v[128:129], s[62:63], 0, v[68:69]
	s_mov_b64 s[62:63], 0x3000
	v_lshl_add_u64 v[152:153], v[128:129], 0, s[62:63]
	s_mov_b64 s[62:63], 0x4000
	s_waitcnt lgkmcnt(0)
	v_add_f32_e32 v111, v111, v130
	ds_bpermute_b32 v132, v93, v111
	v_add_co_u32_e32 v130, vcc, s48, v128
	s_movk_i32 s48, 0x4000
	s_nop 0
	v_addc_co_u32_e32 v131, vcc, 0, v129, vcc
	s_waitcnt lgkmcnt(0)
	v_add_f32_e32 v111, v111, v132
	ds_bpermute_b32 v140, v94, v111
	v_add_co_u32_e32 v132, vcc, s48, v128
	v_lshl_add_u64 v[154:155], v[128:129], 0, s[62:63]
	s_nop 0
	v_addc_co_u32_e32 v133, vcc, 0, v129, vcc
	s_waitcnt lgkmcnt(0)
	v_add_f32_e32 v111, v111, v140
	v_fmamk_f32 v111, v111, 0x3a800000, v210
	v_mul_f32_e32 v140, 0x4b800000, v111
	v_cmp_gt_f32_e32 vcc, s53, v111
	flat_load_dwordx4 v[128:131], v[130:131]
	s_nop 0
	flat_load_dwordx4 v[132:135], v[132:133]
	s_nop 0
	flat_load_dwordx4 v[136:139], v[154:155] offset:1024
	v_cndmask_b32_e32 v111, v111, v140, vcc
	v_rsq_f32_e32 v111, v111
	flat_load_dwordx4 v[140:143], v[152:153] offset:1024
	flat_load_dwordx4 v[144:147], v[152:153] offset:2048
	flat_load_dwordx4 v[148:151], v[154:155] offset:2048
	s_cselect_b32 s48, s43, s51
	s_lshl_b64 s[58:59], s[60:61], 12
	v_mul_f32_e32 v156, 0x45800000, v111
	v_cndmask_b32_e32 v156, v111, v156, vcc
	v_pk_mul_f32 v[88:89], v[156:157], v[88:89] op_sel_hi:[0,1]
	v_pk_mul_f32 v[86:87], v[156:157], v[86:87] op_sel_hi:[0,1]
	s_waitcnt vmcnt(0)
	v_pk_mul_f32 v[86:87], v[2:3], v[86:87]
	v_pk_mul_f32 v[88:89], v[4:5], v[88:89]
	v_pk_mul_f32 v[76:77], v[156:157], v[76:77] op_sel_hi:[0,1]
	v_pk_mul_f32 v[74:75], v[156:157], v[74:75] op_sel_hi:[0,1]
	v_pk_fma_f32 v[48:49], v[122:123], v[88:89], v[48:49]
	v_pk_fma_f32 v[46:47], v[120:121], v[86:87], v[46:47]
	v_pk_mul_f32 v[78:79], v[156:157], v[78:79] op_sel_hi:[0,1]
	v_pk_mul_f32 v[74:75], v[22:23], v[74:75]
	v_pk_mul_f32 v[76:77], v[24:25], v[76:77]
	v_pk_mul_f32 v[84:85], v[156:157], v[84:85] op_sel_hi:[0,1]
	v_pk_mul_f32 v[82:83], v[156:157], v[82:83] op_sel_hi:[0,1]
	v_pk_mul_f32 v[78:79], v[18:19], v[78:79]
	v_pk_fma_f32 v[36:37], v[126:127], v[76:77], v[36:37]
	v_pk_fma_f32 v[34:35], v[124:125], v[74:75], v[34:35]
	v_pk_mul_f32 v[74:75], v[48:49], v[48:49]
	v_pk_mul_f32 v[76:77], v[46:47], v[46:47]
	v_pk_mul_f32 v[82:83], v[6:7], v[82:83]
	v_pk_mul_f32 v[84:85], v[8:9], v[84:85]
	v_pk_fma_f32 v[38:39], v[116:117], v[78:79], v[38:39]
	v_pk_mov_b32 v[78:79], v[76:77], v[74:75] op_sel:[1,0]
	v_mov_b32_e32 v77, v75
	v_pk_fma_f32 v[44:45], v[114:115], v[84:85], v[44:45]
	v_pk_fma_f32 v[42:43], v[112:113], v[82:83], v[42:43]
	v_pk_mul_f32 v[80:81], v[156:157], v[80:81] op_sel_hi:[0,1]
	v_pk_add_f32 v[74:75], v[78:79], v[76:77]
	v_pk_mul_f32 v[80:81], v[20:21], v[80:81]
	v_pk_add_f32 v[74:75], v[74:75], v[74:75] op_sel_hi:[0,1]
	v_pk_mul_f32 v[76:77], v[44:45], v[44:45]
	v_pk_mul_f32 v[78:79], v[42:43], v[42:43]
	v_pk_fma_f32 v[40:41], v[118:119], v[80:81], v[40:41]
	v_pk_mov_b32 v[80:81], v[78:79], v[76:77] op_sel:[1,0]
	v_mov_b32_e32 v79, v77
	v_mul_f32_e32 v74, v38, v38
	v_pk_add_f32 v[76:77], v[80:81], v[78:79]
	v_pk_fma_f32 v[78:79], v[38:39], v[38:39], v[74:75] op_sel_hi:[1,1,0]
	v_mul_f32_e32 v74, v40, v40
	v_pk_add_f32 v[76:77], v[76:77], v[76:77] op_sel_hi:[0,1]
	v_pk_fma_f32 v[80:81], v[40:41], v[40:41], v[74:75] op_sel_hi:[1,1,0]
	v_mul_f32_e32 v78, v34, v34
	v_mul_f32_e32 v80, v35, v35
	v_mul_f32_e32 v74, v36, v36
	v_mul_f32_e32 v76, v37, v37
	v_pk_add_f32 v[78:79], v[78:79], v[80:81]
	v_pk_add_f32 v[74:75], v[74:75], v[76:77]
	s_add_u32 s58, s49, s58
	v_pk_add_f32 v[74:75], v[78:79], v[74:75]
	s_addc_u32 s59, s48, s59
	v_add_f32_e32 v78, v74, v75
	ds_bpermute_b32 v79, v1, v78
	flat_load_dwordx4 v[74:77], v[154:155] offset:3072
	s_waitcnt lgkmcnt(0)
; DI unsigned cvtpk(float lo, float hi) { f32x2_t v = {lo, hi}; bf16x2_t b = __builtin_convertvector(v, bf16x2_t); return __builtin_bit_cast(unsigned, b); }
; DI void rw_phase(const RW& a, int NGW) {
;     ...
;         for (int j = 0; j < 4; ++j) { x[j] = xn[j]; y[j] = yn[j]; }
;     ...
;         if (a.H) {
;             float ss = 0.f;
; #pragma unroll
;             for (int j = 0; j < 4; ++j) ss += (x[j][0] * x[j][0] + x[j][1] * x[j][1]) + (x[j][2] * x[j][2] + x[j][3] * x[j][3]);
;             const float rs = rsqrtf(wave_sum(ss) * (1.f / D) + EPS);
;             bf16_t* hr = a.H + (size_t)r * D;
; #pragma unroll
;             for (int j = 0; j < 4; ++j) { const f32x4 h = (x[j] * rs * gpr[j]) * (s2q[j] + 1.f) + s1q[j];
;                 u32x2 w; w.x = cvtpk(h[0], h[1]); w.y = cvtpk(h[2], h[3]); *(u32x2*)(hr + 4 * lane + 256 * j) = w; }
;         }
;         r = rn;
	v_add_f32_e32 v82, v78, v79
	flat_load_dwordx4 v[78:81], v[152:153] offset:3072
	ds_bpermute_b32 v83, v90, v82
	s_waitcnt lgkmcnt(0)
	v_add_f32_e32 v82, v82, v83
	ds_bpermute_b32 v83, v91, v82
	s_waitcnt lgkmcnt(0)
	v_add_f32_e32 v82, v82, v83
	ds_bpermute_b32 v83, v92, v82
	v_pk_add_f32 v[86:87], v[134:135], 1.0 op_sel_hi:[1,0]
	v_pk_add_f32 v[88:89], v[132:133], 1.0 op_sel_hi:[1,0]
	s_waitcnt lgkmcnt(0)
	v_add_f32_e32 v82, v82, v83
	ds_bpermute_b32 v83, v93, v82
	s_waitcnt lgkmcnt(0)
	v_add_f32_e32 v84, v82, v83
	ds_bpermute_b32 v85, v94, v84
	v_lshl_add_u64 v[82:83], s[58:59], 0, v[68:69]
	flat_store_dwordx4 v[82:83], v[46:49]
	flat_store_dwordx4 v[82:83], v[42:45] offset:1024
	flat_store_dwordx4 v[82:83], v[38:41] offset:2048
	flat_store_dwordx4 v[82:83], v[34:37] offset:3072
	s_waitcnt lgkmcnt(0)
	v_add_f32_e32 v84, v84, v85
	v_fmamk_f32 v84, v84, 0x3a800000, v210
	v_mul_f32_e32 v85, 0x4b800000, v84
	v_cmp_gt_f32_e32 vcc, s53, v84
	s_ashr_i32 s53, s52, 31
	s_lshl_b64 s[52:53], s[52:53], 11
	v_cndmask_b32_e32 v84, v84, v85, vcc
	v_rsq_f32_e32 v84, v84
	s_nop 0
	v_mul_f32_e32 v82, 0x45800000, v84
	v_cndmask_b32_e32 v82, v84, v82, vcc
	v_pk_mul_f32 v[48:49], v[48:49], v[82:83] op_sel_hi:[1,0]
	v_pk_mul_f32 v[46:47], v[46:47], v[82:83] op_sel_hi:[1,0]
	v_pk_mul_f32 v[48:49], v[12:13], v[48:49]
	v_pk_mul_f32 v[46:47], v[10:11], v[46:47]
	v_pk_fma_f32 v[48:49], v[86:87], v[48:49], v[130:131]
	v_pk_fma_f32 v[46:47], v[88:89], v[46:47], v[128:129]
	v_lshl_add_u64 v[84:85], v[72:73], 0, s[52:53]
	v_cvt_pk_bf16_f32 v46, v46, v47
	v_cvt_pk_bf16_f32 v47, v48, v49
	v_pk_mul_f32 v[44:45], v[44:45], v[82:83] op_sel_hi:[1,0]
	v_pk_mul_f32 v[42:43], v[42:43], v[82:83] op_sel_hi:[1,0]
	flat_store_dwordx2 v[84:85], v[46:47]
	v_pk_mul_f32 v[42:43], v[14:15], v[42:43]
	v_pk_mul_f32 v[44:45], v[16:17], v[44:45]
	v_pk_add_f32 v[46:47], v[138:139], 1.0 op_sel_hi:[1,0]
	v_pk_add_f32 v[48:49], v[136:137], 1.0 op_sel_hi:[1,0]
	v_pk_fma_f32 v[44:45], v[46:47], v[44:45], v[142:143]
	v_pk_fma_f32 v[42:43], v[48:49], v[42:43], v[140:141]
	v_pk_mul_f32 v[40:41], v[40:41], v[82:83] op_sel_hi:[1,0]
	v_cvt_pk_bf16_f32 v42, v42, v43
	v_cvt_pk_bf16_f32 v43, v44, v45
	v_pk_mul_f32 v[38:39], v[38:39], v[82:83] op_sel_hi:[1,0]
	flat_store_dwordx2 v[84:85], v[42:43] offset:512
	v_pk_mul_f32 v[38:39], v[26:27], v[38:39]
	v_pk_mul_f32 v[40:41], v[28:29], v[40:41]
	v_pk_add_f32 v[42:43], v[150:151], 1.0 op_sel_hi:[1,0]
	v_pk_add_f32 v[44:45], v[148:149], 1.0 op_sel_hi:[1,0]
	v_pk_fma_f32 v[40:41], v[42:43], v[40:41], v[146:147]
	v_pk_fma_f32 v[38:39], v[44:45], v[38:39], v[144:145]
	v_pk_mul_f32 v[36:37], v[36:37], v[82:83] op_sel_hi:[1,0]
	v_cvt_pk_bf16_f32 v38, v38, v39
	v_cvt_pk_bf16_f32 v39, v40, v41
	v_pk_mul_f32 v[34:35], v[34:35], v[82:83] op_sel_hi:[1,0]
	flat_store_dwordx2 v[84:85], v[38:39] offset:1024
	v_pk_mul_f32 v[34:35], v[30:31], v[34:35]
	v_pk_mul_f32 v[36:37], v[32:33], v[36:37]
	s_waitcnt vmcnt(0)
	v_pk_add_f32 v[38:39], v[76:77], 1.0 op_sel_hi:[1,0]
	v_pk_add_f32 v[40:41], v[74:75], 1.0 op_sel_hi:[1,0]
	v_pk_fma_f32 v[36:37], v[38:39], v[36:37], v[80:81]
	v_pk_fma_f32 v[34:35], v[40:41], v[34:35], v[78:79]
	v_lshlrev_b32_e32 v98, 16, v160
	v_and_b32_e32 v97, 0xffff0000, v160
	v_lshlrev_b32_e32 v96, 16, v161
	v_and_b32_e32 v95, 0xffff0000, v161
	v_lshlrev_b32_e32 v102, 16, v162
	v_and_b32_e32 v101, 0xffff0000, v162
	v_lshlrev_b32_e32 v100, 16, v163
	v_and_b32_e32 v99, 0xffff0000, v163
	v_lshlrev_b32_e32 v106, 16, v164
	v_and_b32_e32 v105, 0xffff0000, v164
	v_lshlrev_b32_e32 v104, 16, v165
	v_and_b32_e32 v103, 0xffff0000, v165
	v_lshlrev_b32_e32 v110, 16, v166
	v_and_b32_e32 v109, 0xffff0000, v166
	v_lshlrev_b32_e32 v108, 16, v167
	v_and_b32_e32 v107, 0xffff0000, v167
	v_mov_b64_e32 v[46:47], v[62:63]
	v_cvt_pk_bf16_f32 v34, v34, v35
	v_cvt_pk_bf16_f32 v35, v36, v37
	flat_store_dwordx2 v[84:85], v[34:35] offset:1536
	v_mov_b64_e32 v[42:43], v[58:59]
	v_mov_b64_e32 v[38:39], v[54:55]
	v_mov_b64_e32 v[34:35], v[50:51]
	s_andn2_b64 vcc, exec, s[56:57]
	v_mov_b64_e32 v[48:49], v[64:65]
	v_mov_b64_e32 v[44:45], v[60:61]
	v_mov_b64_e32 v[40:41], v[56:57]
	v_mov_b64_e32 v[36:37], v[52:53]
	s_mov_b32 s52, s54
	v_mov_b32_e32 v86, v98
	v_mov_b32_e32 v87, v97
	v_mov_b32_e32 v88, v96
	v_mov_b32_e32 v89, v95
	v_mov_b32_e32 v82, v102
	v_mov_b32_e32 v83, v101
	v_mov_b32_e32 v84, v100
	v_mov_b32_e32 v85, v99
	v_mov_b32_e32 v78, v106
	v_mov_b32_e32 v79, v105
	v_mov_b32_e32 v80, v104
	v_mov_b32_e32 v81, v103
	v_mov_b32_e32 v74, v110
	v_mov_b32_e32 v75, v109
	v_mov_b32_e32 v76, v108
	v_mov_b32_e32 v77, v107
	s_cbranch_vccz .LBB0_1030

; DI void rw_phase(const RW& a, int NGW) {
;     ...
;         f32x4 x[4], y[4];
; #pragma unroll
;         for (int j = 0; j < 4; ++j) { x[j] = xn[j]; y[j] = yn[j]; }
.LBB0_1280:
	v_lshlrev_b32_e32 v144, 16, v174
	v_and_b32_e32 v143, 0xffff0000, v174
	v_lshlrev_b32_e32 v142, 16, v175
	v_and_b32_e32 v141, 0xffff0000, v175
	v_lshlrev_b32_e32 v148, 16, v168
	v_and_b32_e32 v147, 0xffff0000, v168
	v_lshlrev_b32_e32 v146, 16, v169
	v_and_b32_e32 v145, 0xffff0000, v169
	v_lshlrev_b32_e32 v152, 16, v170
	v_and_b32_e32 v151, 0xffff0000, v170
	v_lshlrev_b32_e32 v150, 16, v171
	v_and_b32_e32 v149, 0xffff0000, v171
	v_lshlrev_b32_e32 v156, 16, v172
	v_and_b32_e32 v155, 0xffff0000, v172
	v_lshlrev_b32_e32 v154, 16, v173
	v_and_b32_e32 v153, 0xffff0000, v173
	v_mov_b64_e32 v[78:79], v[94:95]
	v_mov_b64_e32 v[74:75], v[90:91]
	v_mov_b64_e32 v[70:71], v[86:87]
	v_mov_b64_e32 v[66:67], v[82:83]
	s_andn2_b64 vcc, exec, s[46:47]
	v_mov_b64_e32 v[80:81], v[96:97]
	v_mov_b64_e32 v[76:77], v[92:93]
	v_mov_b64_e32 v[72:73], v[88:89]
	v_mov_b64_e32 v[68:69], v[84:85]
	s_mov_b32 s54, s42
	v_mov_b32_e32 v132, v144
	v_mov_b32_e32 v133, v143
	v_mov_b32_e32 v134, v142
	v_mov_b32_e32 v135, v141
	v_mov_b32_e32 v128, v148
	v_mov_b32_e32 v129, v147
	v_mov_b32_e32 v130, v146
	v_mov_b32_e32 v131, v145
	v_mov_b32_e32 v124, v152
	v_mov_b32_e32 v125, v151
	v_mov_b32_e32 v126, v150
	v_mov_b32_e32 v127, v149
	v_mov_b32_e32 v120, v156
	v_mov_b32_e32 v121, v155
	v_mov_b32_e32 v122, v154
	v_mov_b32_e32 v123, v153
	s_cbranch_vccz .LBB0_1299

; DI void rw_phase(const RW& a, int NGW) {
;     ...
;         int rn = r + NGW;
;         if (a.skipctx) { while (rn < M && (rn % TP) >= TL) rn += NGW; }
;         if (rn < M) RW_LOAD(rn);
.LBB0_1291:
	s_ashr_i32 s63, s62, 31
	s_lshl_b64 s[62:63], s[62:63], 12
	s_add_u32 s62, s64, s62
	s_addc_u32 s63, s65, s63
	s_ashr_i32 s43, s42, 31
	v_lshl_add_u64 v[82:83], v[114:115], 2, s[62:63]
	s_lshl_b64 s[62:63], s[42:43], 11
	v_lshl_add_u64 v[98:99], v[116:117], 0, s[62:63]
	flat_load_dwordx4 v[94:97], v[82:83]
	flat_load_dwordx4 v[90:93], v[82:83] offset:1024
	flat_load_dwordx4 v[86:89], v[82:83] offset:2048
	s_nop 0
	flat_load_dwordx4 v[82:85], v[82:83] offset:3072
	v_readlane_b32 s64, v254, 45
	v_readlane_b32 s65, v254, 46
	flat_load_dwordx2 v[174:175], v[98:99]
	flat_load_dwordx2 v[168:169], v[98:99] offset:512
	flat_load_dwordx2 v[170:171], v[98:99] offset:1024
	flat_load_dwordx2 v[172:173], v[98:99] offset:1536
